# A2 diff-attn: V^T LDS rows repitched 264->272B, keys permuted per 16-key group, PV fragment reads ds_read2_b64 -> conflict-free ds_read_b128
# baseline (speedup 1.0000x reference)
;     constexpr int NKB = MODE ? 2 : 4, NSUB = MODE ? 2 : 1, KT = 32 * NKB * NSUB;
;     constexpr int DV = MODE ? 128 : 64, NDB = DV / 32;
;     constexpr int KP = MODE ? 272 : 144, VP = 2 * KT + 8;
;     constexpr int KBYTES = KT * KP, VBYTES = DV * VP, STAGE = KBYTES + VBYTES;
;     constexpr int KCH = MODE ? 16 : 8, VCH = KT / 8;
;     constexpr int NKL = KT * KCH / 512, NVL = DV * VCH / 512;
;     static_assert(2 * STAGE <= LDS_BYTES - 64 && NKL >= 1 && NVL >= 1, "attention LDS stages");
;     const int r = lane & 31, h = lane >> 5;
;     const size_t rowbase = (size_t)b * SEQ;
;     float zf_ = 0.f; asm volatile("" : "+v"(zf_));
;     int q0, ntiles, qcol, kcol, koff; const bf16_t* vtbase;
;     if (MODE == 0) { q0 = qb * 32; ntiles = (q0 + 31) / KT + 1; qcol = C_QA + wave * 64; kcol = C_KA; koff = 0; vtbase = VT + (size_t)b * 64 * SEQ; }
;     else { const int map = wave >> 2, sub = wave & 3; q0 = qb * 128 + sub * 32; ntiles = (qb * 128 + 127) / KT + 1; qcol = C_QB + (hd * 2 + map) * 64; kcol = C_KB + hd * 128; koff = map * 128; vtbase = VT + (size_t)(b * 4 + hd) * 128 * SEQ; }
;     const bf16_t* qrow = PROJ + (rowbase + q0 + r) * NINP + qcol;
;     bf16x8 qf[4];
; #pragma unroll
;     for (int ks = 0; ks < 4; ++ks) qf[ks] = *(const bf16x8*)(qrow + ks * 16 + h * 8);
;     f32x16 ot[NDB];
; #pragma unroll
;     for (int db = 0; db < NDB; ++db)
; #pragma unroll
;         for (int i = 0; i < 16; ++i) ot[db][i] = zf_;
;     float nm_run = zf_, l_run = 0.f;
;     u32x4 kreg[NKL], vreg[NVL];
; __global__ void __launch_bounds__(NTHR, 2) hybrid_fwd(Args a_unused) {
;     ...
;             const float lam_init = l == 0 ? 0.2f : 0.35550906759f;
;             const float sa = wave_sum(ap->in[8][l * 64 + lane] * ap->in[9][l * 64 + lane], lane), sb = wave_sum(ap->in[10][l * 64 + lane] * ap->in[11][l * 64 + lane], lane);
;             const float lam = __builtin_amdgcn_exp2f(sa * 1.4426950408889634f) - __builtin_amdgcn_exp2f(sb * 1.4426950408889634f) + lam_init;
; #pragma unroll 1
;             for (int k = 0; vcu + (k >> 1) * G < NB * 4 * 8; ++k) { const int u = k, pr = vcu + (k >> 1) * G, b = pr >> 5, hd = (pr >> 3) & 3, j = pr & 7;
;                 attn_unit<1>(PROJ_, PROJ_ + C_QB, NINP, (const bf16_t*)(ws + WS_VTB), nullptr, lds, b, hd, (u & 1) ? j : 15 - j, ap->in[12] + l * 128, lam, 1.f - lam_init, tid, wave, lane); }
.LBB0_493:
	v_readlane_b32 s66, v253, 0
	v_readlane_b32 s67, v253, 1
	s_mov_b64 s[0:1], s[66:67]
	s_mov_b32 s12, s73
	s_barrier
	v_mbcnt_lo_u32_b32 v0, -1, 0
	v_mbcnt_hi_u32_b32 v0, -1, v0
	s_load_dwordx8 s[4:11], s[0:1], 0x40
	v_readlane_b32 s2, v253, 46
	v_lshlrev_b32_e32 v6, 2, v0
	v_xor_b32_e32 v8, 4, v6
	v_lshl_add_u32 v2, s2, 6, v0
	v_ashrrev_i32_e32 v3, 31, v2
	v_lshlrev_b64 v[4:5], 2, v[2:3]
	s_waitcnt lgkmcnt(0)
	v_lshl_add_u64 v[2:3], s[4:5], 0, v[4:5]
	global_load_dword v1, v[2:3], off
	v_lshl_add_u64 v[2:3], s[6:7], 0, v[4:5]
	global_load_dword v2, v[2:3], off
	v_xor_b32_e32 v9, 8, v6
	v_xor_b32_e32 v10, 32, v6
	v_xor_b32_e32 v11, 64, v6
	v_xor_b32_e32 v99, 0x80, v6
	v_readlane_b32 s3, v253, 47
	v_readlane_b32 s2, v253, 20
	v_readlane_b32 s3, v253, 21
	v_readlane_b32 s82, v253, 59
	s_and_b64 vcc, exec, s[2:3]
	v_readlane_b32 s83, v253, 60
	v_readlane_b32 s69, v254, 0
	v_readlane_b32 s29, v253, 19
	s_mov_b32 s30, 0xf800000
	s_waitcnt vmcnt(0)
	v_mul_f32_e32 v3, v1, v2
	ds_bpermute_b32 v3, v8, v3
	s_waitcnt lgkmcnt(0)
	v_fmac_f32_e32 v3, v1, v2
	ds_bpermute_b32 v1, v9, v3
	s_waitcnt lgkmcnt(0)
	v_add_f32_e32 v1, v3, v1
	v_xor_b32_e32 v3, 16, v6
	v_lshl_add_u64 v[6:7], s[8:9], 0, v[4:5]
	v_lshl_add_u64 v[4:5], s[10:11], 0, v[4:5]
	global_load_dword v6, v[6:7], off
	ds_bpermute_b32 v2, v3, v1
	global_load_dword v4, v[4:5], off
	s_waitcnt lgkmcnt(0)
	v_add_f32_e32 v1, v1, v2
	ds_bpermute_b32 v2, v10, v1
	s_waitcnt lgkmcnt(0)
	v_add_f32_e32 v1, v1, v2
	ds_bpermute_b32 v2, v11, v1
	s_waitcnt lgkmcnt(0)
	v_add_f32_e32 v1, v1, v2
	ds_bpermute_b32 v2, v99, v1
	s_waitcnt vmcnt(0)
	v_mul_f32_e32 v5, v6, v4
	ds_bpermute_b32 v5, v8, v5
	s_waitcnt lgkmcnt(0)
	v_fmac_f32_e32 v5, v6, v4
	ds_bpermute_b32 v4, v9, v5
	s_waitcnt lgkmcnt(0)
	v_add_f32_e32 v4, v5, v4
	ds_bpermute_b32 v3, v3, v4
	s_waitcnt lgkmcnt(0)
	v_add_f32_e32 v3, v4, v3
	ds_bpermute_b32 v4, v10, v3
	s_waitcnt lgkmcnt(0)
	v_add_f32_e32 v3, v3, v4
	ds_bpermute_b32 v4, v11, v3
	s_waitcnt lgkmcnt(0)
	v_add_f32_e32 v3, v3, v4
	ds_bpermute_b32 v4, v99, v3
	s_cbranch_vccz .LBB0_515
	v_add_f32_e32 v1, v1, v2
	s_waitcnt lgkmcnt(0)
	v_add_f32_e32 v2, v3, v4
	v_mul_f32_e32 v1, 0x3fb8aa3b, v1
	v_mul_f32_e32 v2, 0x3fb8aa3b, v2
	s_load_dwordx2 s[6:7], s[0:1], 0xc8
	v_exp_f32_e32 v1, v1
	v_exp_f32_e32 v2, v2
	v_readlane_b32 s2, v253, 44
	v_mov_b32_e32 v3, 0x3eb60549
	v_mov_b32_e32 v4, 0x3e4ccccd
	v_readlane_b32 s3, v253, 45
	v_sub_f32_e32 v1, v1, v2
	s_load_dwordx2 s[0:1], s[0:1], 0x60
	v_cndmask_b32_e64 v3, v3, v4, s[2:3]
	s_waitcnt lgkmcnt(0)
	s_add_u32 s2, s6, 0x9200000
	v_add_f32_e32 v148, v3, v1
	v_lshl_add_u32 v1, s12, 6, v0
	s_addc_u32 s3, s7, 0
	s_add_u32 s4, s6, 0x9200780
	v_add_u32_e32 v6, 0x200, v1
	s_addc_u32 s5, s7, 0
	v_ashrrev_i32_e32 v7, 31, v6
	s_add_u32 s14, s6, 0x1b600000
	v_lshrrev_b32_e32 v7, 28, v7
	s_addc_u32 s15, s7, 0
	v_readlane_b32 s6, v253, 46
	v_add_u32_e32 v7, v6, v7
	v_readlane_b32 s7, v253, 47
	s_lshl_b32 s74, s6, 7
	v_ashrrev_i32_e32 v156, 4, v7
	v_and_b32_e32 v7, -16, v7
	s_lshl_b64 s[6:7], s[74:75], 2
	v_sub_u32_e32 v8, v6, v7
	s_add_u32 s0, s0, s6
	s_movk_i32 s10, 0x110
	v_lshlrev_b32_e32 v6, 3, v8
	v_lshlrev_b32_e32 v8, 4, v8
	s_addc_u32 s1, s1, s7
	v_mad_u64_u32 v[158:159], s[6:7], v156, s10, v[8:9]
	v_add_u32_e32 v9, 0x400, v1
	v_ashrrev_i32_e32 v2, 31, v1
	v_ashrrev_i32_e32 v10, 31, v9
	v_lshrrev_b32_e32 v2, 28, v2
	v_lshrrev_b32_e32 v10, 28, v10
	v_add_u32_e32 v2, v1, v2
	v_add_u32_e32 v10, v9, v10
	v_ashrrev_i32_e32 v152, 4, v2
	v_and_b32_e32 v2, -16, v2
	v_ashrrev_i32_e32 v160, 4, v10
	v_and_b32_e32 v10, -16, v10
	v_sub_u32_e32 v4, v1, v2
	v_sub_u32_e32 v9, v9, v10
	v_add_u32_e32 v1, 0x600, v1
	v_lshlrev_b32_e32 v10, 3, v9
	v_lshlrev_b32_e32 v12, 4, v9
	v_ashrrev_i32_e32 v9, 31, v1
	v_lshrrev_b32_e32 v9, 28, v9
	v_add_u32_e32 v9, v1, v9
	v_ashrrev_i32_e32 v164, 4, v9
	v_and_b32_e32 v9, -16, v9
	v_ashrrev_i32_e32 v5, 5, v0
	v_lshlrev_b32_e32 v2, 3, v4
	v_lshlrev_b32_e32 v4, 4, v4
	v_sub_u32_e32 v1, v1, v9
	v_mad_u64_u32 v[154:155], s[6:7], v152, s10, v[4:5]
	v_lshlrev_b32_e32 v14, 3, v1
	v_lshlrev_b32_e32 v16, 4, v1
	v_lshlrev_b32_e32 v1, 3, v152
	v_and_b32_e32 v211, 31, v0
	v_and_b32_e32 v248, 1, v0
	v_lshlrev_b32_e32 v248, 3, v248
	s_and_b32 s9, s12, 3
	v_mad_u64_u32 v[162:163], s[6:7], v160, s10, v[12:13]
	v_sub_u32_e32 v1, v154, v248
	v_lshlrev_b32_e32 v9, 3, v156
	v_lshlrev_b32_e32 v168, 2, v5
	v_lshl_add_u32 v0, v0, 2, 0
	s_ashr_i32 s8, s12, 2
	v_mad_u64_u32 v[166:167], s[6:7], v164, s10, v[16:17]
	v_sub_u32_e32 v9, v158, v248
	v_lshlrev_b32_e32 v13, 3, v160
	v_lshl_add_u32 v159, s9, 14, v0
	v_lshl_add_u32 v163, s12, 14, v0
	v_ashrrev_i32_e32 v169, 31, v168
	s_movk_i32 s10, 0x108
	v_add_u32_e32 v0, 0, v1
	s_lshl_b32 s16, s9, 5
	s_lshl_b32 s17, s8, 6
	s_lshl_b32 s18, s8, 7
	v_sub_u32_e32 v13, v162, v248
	v_lshlrev_b32_e32 v17, 3, v164
	v_lshl_add_u64 v[170:171], v[168:169], 2, s[0:1]
	v_mad_u64_u32 v[172:173], s[0:1], v152, s10, v[4:5]
	v_add_u32_e32 v167, 0x8800, v0
	v_add_u32_e32 v0, 0, v9
	v_sub_u32_e32 v17, v166, v248
	s_cmp_eq_u32 s8, 1
	v_mad_u64_u32 v[174:175], s[0:1], v156, s10, v[8:9]
	v_add_u32_e32 v173, 0x8800, v0
	v_add_u32_e32 v0, 0, v13
	v_sub_f32_e32 v210, 1.0, v3
	v_lshlrev_b32_e32 v150, 3, v5
	v_ashrrev_i32_e32 v3, 31, v2
	v_ashrrev_i32_e32 v7, 31, v6
	v_ashrrev_i32_e32 v11, 31, v10
	v_ashrrev_i32_e32 v15, 31, v14
	s_cselect_b64 s[6:7], -1, 0
	s_cmp_lt_u32 s12, 4
	v_mad_u64_u32 v[176:177], s[0:1], v160, s10, v[12:13]
	v_mad_u64_u32 v[178:179], s[0:1], v164, s10, v[16:17]
	v_lshl_add_u32 v172, v152, 3, v172
	v_sub_u32_e32 v172, v172, v248
	v_lshl_add_u32 v174, v156, 3, v174
	v_sub_u32_e32 v174, v174, v248
	v_lshl_add_u32 v176, v160, 3, v176
	v_sub_u32_e32 v176, v176, v248
	v_lshl_add_u32 v178, v164, 3, v178
	v_sub_u32_e32 v178, v178, v248
	v_add_u32_e32 v175, 0x8800, v0
	v_add_u32_e32 v0, 0, v17
	v_ashrrev_i32_e32 v151, 31, v150
	v_ashrrev_i32_e32 v153, 31, v152
	v_ashrrev_i32_e32 v157, 31, v156
	v_ashrrev_i32_e32 v161, 31, v160
	v_ashrrev_i32_e32 v165, 31, v164
	v_lshlrev_b32_e32 v155, 4, v5
	s_cselect_b64 s[8:9], -1, 0
	v_mov_b32_e32 v149, v148
	s_mov_b32 s19, 0
	v_lshlrev_b64 v[180:181], 1, v[2:3]
	v_lshlrev_b64 v[182:183], 1, v[6:7]
	v_lshlrev_b64 v[184:185], 1, v[10:11]
	v_lshlrev_b64 v[186:187], 1, v[14:15]
	v_add_u32_e32 v177, 0x8800, v0
	s_mov_b32 s0, s29
	s_branch .LBB0_496

; #define ATT_LOAD(kt) do { _Pragma("unroll") for (int p = 0; p < NKL; ++p) kreg[p] = *(const u32x4*)(kg[p] + (size_t)(kt) * KT * NINP); \
;                           _Pragma("unroll") for (int p = 0; p < NVL; ++p) vreg[p] = *(const u32x4*)(vg[p] + (kt) * KT); } while (0)
;     ...
;     if (MODE == 0) { q0 = qb * 32; ntiles = (q0 + 31) / KT + 1; qcol = C_QA + wave * 64; kcol = C_KA; koff = 0; vtbase = VT + (size_t)b * 64 * SEQ; }
;     else { const int map = wave >> 2, sub = wave & 3; q0 = qb * 128 + sub * 32; ntiles = (qb * 128 + 127) / KT + 1; qcol = C_QB + (hd * 2 + map) * 64; kcol = C_KB + hd * 128; koff = map * 128; vtbase = VT + (size_t)(b * 4 + hd) * 128 * SEQ; }
;     const bf16_t* qrow = PROJ + (rowbase + q0 + r) * NINP + qcol;
;     bf16x8 qf[4];
; #pragma unroll
;     for (int ks = 0; ks < 4; ++ks) qf[ks] = *(const bf16x8*)(qrow + ks * 16 + h * 8);
;     f32x16 ot[NDB];
; #pragma unroll
;     for (int db = 0; db < NDB; ++db)
; #pragma unroll
;         for (int i = 0; i < 16; ++i) ot[db][i] = zf_;
;     float nm_run = zf_, l_run = 0.f;
;     u32x4 kreg[NKL], vreg[NVL];
;     const bf16_t* kg[NKL]; const bf16_t* vg[NVL]; int klds[NKL], vlds[NVL];
; #pragma unroll
;     for (int p = 0; p < NKL; ++p) { const int idx = tid + 512 * p; const int row = idx / KCH, ch = idx % KCH;
;         kg[p] = PROJ + (rowbase + row) * NINP + kcol + ch * 8; klds[p] = row * KP + ch * 16; }
; #pragma unroll
;     for (int p = 0; p < NVL; ++p) { const int idx = tid + 512 * p; const int d = idx / VCH, ch = idx % VCH;
;         vg[p] = vtbase + (size_t)d * SEQ + ch * 8; vlds[p] = KBYTES + d * VP + ch * 16; }
;     ...
;     ATT_LOAD(0); ATT_STORE(0);
;     __syncthreads();
.LBB0_496:
	s_ashr_i32 s12, s0, 5
	s_bfe_u32 s23, s0, 0x20003
	s_and_b32 s0, s0, 7
	s_and_b32 s1, s19, 1
	s_xor_b32 s10, s0, 15
	s_cmp_eq_u32 s1, 0
	s_cselect_b32 s21, s10, s0
	s_ashr_i32 s13, s12, 31
	s_lshl_b32 s11, s12, 2
	s_lshl_b64 s[0:1], s[12:13], 11
	s_lshl_b32 s10, s21, 7
	s_lshl_b32 s20, s23, 7
	s_or_b32 s12, s11, s23
	s_or_b32 s22, s10, s16
	s_add_i32 s10, s20, s17
	s_ashr_i32 s13, s12, 31
	s_lshl_b64 s[12:13], s[12:13], 19
	s_ashr_i32 s11, s10, 31
	s_lshl_b32 s23, s23, 8
	s_add_u32 s24, s2, s23
	s_addc_u32 s25, s3, 0
	v_lshl_add_u64 v[2:3], s[0:1], 0, v[152:153]
	v_mov_b64_e32 v[4:5], s[24:25]
	v_mad_u64_u32 v[6:7], s[24:25], v2, s90, v[4:5]
	v_mad_i32_i24 v7, v3, s90, v7
	v_lshl_add_u64 v[2:3], s[0:1], 0, v[156:157]
	v_lshl_add_u64 v[190:191], v[6:7], 0, v[180:181]
	v_mad_u64_u32 v[6:7], s[24:25], v2, s90, v[4:5]
	v_mad_i32_i24 v7, v3, s90, v7
	v_lshl_add_u64 v[2:3], s[0:1], 0, v[160:161]
	v_lshl_add_u64 v[192:193], v[6:7], 0, v[182:183]
	v_mad_u64_u32 v[6:7], s[24:25], v2, s90, v[4:5]
	v_mad_i32_i24 v7, v3, s90, v7
	v_lshl_add_u64 v[2:3], s[0:1], 0, v[164:165]
	v_mad_u64_u32 v[4:5], s[24:25], v2, s90, v[4:5]
	s_add_u32 s12, s14, s12
	v_mad_i32_i24 v5, v3, s90, v5
	s_addc_u32 s13, s15, s13
	v_lshlrev_b64 v[2:3], 12, v[152:153]
	v_lshl_add_u64 v[2:3], s[12:13], 0, v[2:3]
	v_lshl_add_u64 v[202:203], v[2:3], 0, v[180:181]
	v_lshlrev_b64 v[2:3], 12, v[156:157]
	v_lshl_add_u64 v[2:3], s[12:13], 0, v[2:3]
	v_lshl_add_u64 v[204:205], v[2:3], 0, v[182:183]
	v_lshlrev_b64 v[2:3], 12, v[160:161]
	v_lshl_add_u64 v[2:3], s[12:13], 0, v[2:3]
	v_lshl_add_u64 v[206:207], v[2:3], 0, v[184:185]
	v_lshlrev_b64 v[2:3], 12, v[164:165]
	v_lshl_add_u64 v[2:3], s[12:13], 0, v[2:3]
	v_or_b32_e32 v179, s22, v211
	v_lshl_add_u64 v[208:209], v[2:3], 0, v[186:187]
	v_or_b32_e32 v1, s0, v179
	v_mov_b64_e32 v[2:3], s[2:3]
	v_mov_b32_e32 v0, v98
	v_lshl_add_u64 v[200:201], v[4:5], 0, v[186:187]
	v_mad_u64_u32 v[2:3], s[12:13], v1, s90, v[2:3]
	v_mov_b32_e32 v4, 0x2400
	global_load_dwordx4 v[100:103], v[190:191], off offset:2944
	global_load_dwordx4 v[104:107], v[192:193], off offset:2944
	v_mad_i32_i24 v3, s1, v4, v3
	v_lshl_add_u64 v[194:195], v[6:7], 0, v[184:185]
	v_lshl_add_u64 v[2:3], s[10:11], 1, v[2:3]
	global_load_dwordx4 v[108:111], v[194:195], off offset:2944
	v_lshl_add_u64 v[2:3], v[150:151], 1, v[2:3]
	global_load_dwordx4 v[112:115], v[200:201], off offset:2944
	global_load_dwordx4 v[132:135], v[202:203], off
	global_load_dwordx4 v[136:139], v[204:205], off
	global_load_dwordx4 v[140:143], v[206:207], off
	global_load_dwordx4 v[144:147], v[208:209], off
	global_load_dwordx4 v[116:119], v[2:3], off offset:1920
	global_load_dwordx4 v[120:123], v[2:3], off offset:1952
	global_load_dwordx4 v[124:127], v[2:3], off offset:1984
	global_load_dwordx4 v[128:131], v[2:3], off offset:2016
	v_add_u32_e32 v16, 0, v154
	v_mov_b32_e32 v14, v0
	v_mov_b32_e32 v15, v0
	v_mad_u64_u32 v[188:189], s[10:11], v1, s90, 0
	s_mul_i32 s0, s1, 0x2400
	v_mov_b32_e32 v1, v0
	v_mov_b32_e32 v2, v0
	v_mov_b32_e32 v3, v0
	v_mov_b32_e32 v4, v0
	v_mov_b32_e32 v5, v0
	v_mov_b32_e32 v6, v0
	v_mov_b32_e32 v7, v0
	v_mov_b32_e32 v8, v0
	v_mov_b32_e32 v9, v0
	v_mov_b32_e32 v10, v0
	v_mov_b32_e32 v11, v0
	v_mov_b32_e32 v12, v0
	v_mov_b32_e32 v13, v0
	v_mov_b64_e32 v[62:63], v[14:15]
	v_mov_b64_e32 v[46:47], v[14:15]
	v_add_u32_e32 v189, s0, v189
	s_or_b32 s23, s22, 31
	v_subrev_u32_e32 v213, 58, v179
	v_subrev_u32_e32 v214, 59, v179
	v_mov_b32_e32 v212, 0
	v_mov_b64_e32 v[60:61], v[12:13]
	v_mov_b64_e32 v[58:59], v[10:11]
	v_mov_b64_e32 v[56:57], v[8:9]
	v_mov_b64_e32 v[54:55], v[6:7]
	v_mov_b64_e32 v[52:53], v[4:5]
	v_mov_b64_e32 v[50:51], v[2:3]
	v_mov_b64_e32 v[48:49], v[0:1]
	v_mov_b64_e32 v[44:45], v[12:13]
	v_mov_b64_e32 v[42:43], v[10:11]
	v_mov_b64_e32 v[40:41], v[8:9]
	v_mov_b64_e32 v[38:39], v[6:7]
	v_mov_b64_e32 v[36:37], v[4:5]
	v_mov_b64_e32 v[34:35], v[2:3]
	v_mov_b64_e32 v[32:33], v[0:1]
	v_mov_b32_e32 v64, v0
	s_mov_b32 s24, 0
	s_waitcnt vmcnt(11)
	ds_write_b128 v16, v[100:103]
	v_add_u32_e32 v16, 0, v158
	s_waitcnt vmcnt(10)
	ds_write_b128 v16, v[104:107]
	v_add_u32_e32 v16, 0, v162
	s_waitcnt vmcnt(9)
	ds_write_b128 v16, v[108:111]
	v_add_u32_e32 v16, 0, v166
	s_waitcnt vmcnt(8)
	ds_write_b128 v16, v[112:115]
	s_waitcnt vmcnt(7)
	ds_write2_b64 v167, v[132:133], v[134:135] offset1:2
	s_waitcnt vmcnt(6)
	ds_write2_b64 v173, v[136:137], v[138:139] offset1:2
	s_waitcnt vmcnt(5)
	ds_write2_b64 v175, v[140:141], v[142:143] offset1:2
	s_waitcnt vmcnt(4)
	ds_write2_b64 v177, v[144:145], v[146:147] offset1:2
	v_mov_b64_e32 v[30:31], v[14:15]
	v_mov_b64_e32 v[28:29], v[12:13]
	v_mov_b64_e32 v[26:27], v[10:11]
	v_mov_b64_e32 v[24:25], v[8:9]
	v_mov_b64_e32 v[22:23], v[6:7]
	v_mov_b64_e32 v[20:21], v[4:5]
	v_mov_b64_e32 v[18:19], v[2:3]
	v_mov_b64_e32 v[16:17], v[0:1]
	s_waitcnt lgkmcnt(0)
	s_barrier

; #define LAS __attribute__((address_space(3)))
; DI unsigned pk2(float a, float b) { f32x2 v = {a, b}; bf16x2_t r = __builtin_convertvector(v, bf16x2_t); return __builtin_bit_cast(unsigned, r); }
; #define MFMA32(a, b, c) __builtin_amdgcn_mfma_f32_32x32x16_bf16((a), (b), (c), 0, 0, 0)
;     ...
;             float ps = 0.f;
; #pragma unroll
;             for (int kb2 = 0; kb2 < NKB; ++kb2)
; #pragma unroll
;                 for (int i = 0; i < 16; ++i) { sv[kb2][i] = __builtin_amdgcn_exp2f(sv[kb2][i]); ps += sv[kb2][i]; }
;             l_run += ps;
;             const LAS unsigned char* vb_ = lds + st * STAGE + KBYTES + sub * 32 * NKB * 2;
; #pragma unroll
;             for (int kb2 = 0; kb2 < NKB; ++kb2)
; #pragma unroll
;                 for (int s = 0; s < 2; ++s) {
;                     u32x2 vlo[NDB], vhi[NDB];
; #pragma unroll
;                     for (int db = 0; db < NDB; ++db) { const LAS unsigned char* vp = vb_ + (32 * db + r) * VP + (32 * kb2 + 16 * s + 4 * h) * 2;
;                         vlo[db] = *(const LAS u32x2*)vp; vhi[db] = *(const LAS u32x2*)(vp + 16); }
;                     u32x4 pw;
;                     pw.x = pk2(sv[kb2][8 * s + 0], sv[kb2][8 * s + 1]); pw.y = pk2(sv[kb2][8 * s + 2], sv[kb2][8 * s + 3]); pw.z = pk2(sv[kb2][8 * s + 4], sv[kb2][8 * s + 5]); pw.w = pk2(sv[kb2][8 * s + 6], sv[kb2][8 * s + 7]);
;                     const bf16x8 pf = __builtin_bit_cast(bf16x8, pw);
;                     if (NDB == 2) asm volatile("" : "+v"(vlo[0]), "+v"(vhi[0]), "+v"(vlo[1]), "+v"(vhi[1]));
;                     else asm volatile("" : "+v"(vlo[0]), "+v"(vhi[0]), "+v"(vlo[1]), "+v"(vhi[1]), "+v"(vlo[NDB - 2]), "+v"(vhi[NDB - 2]), "+v"(vlo[NDB - 1]), "+v"(vhi[NDB - 1]));
; #pragma unroll
;                     for (int db = 0; db < NDB; ++db) { const u32x4 vw = {vlo[db].x, vlo[db].y, vhi[db].x, vhi[db].y};
;                         ot[db] = MFMA32(__builtin_bit_cast(bf16x8, vw), pf, ot[db]); }
;                 }
.LBB0_499:
	s_and_b32 s26, s24, 1
	s_mul_i32 s10, s26, 0x11000
	s_add_i32 s10, s10, 0
	s_add_i32 s11, s10, s18
	s_lshl_b32 s27, s24, 7
	v_add_u32_e32 v215, s11, v155
	v_add_u32_e32 v216, s10, v155
	s_mov_b32 s28, 0
	s_mov_b64 s[10:11], -1
	s_branch .LBB0_502
.LBB0_500:
	v_exp_f32_e32 v196, v82
	v_exp_f32_e32 v197, v83
	v_exp_f32_e32 v217, v84
	v_exp_f32_e32 v219, v85
	v_add_f32_e32 v65, 0, v196
	v_exp_f32_e32 v220, v86
	v_add_f32_e32 v65, v197, v65
	v_exp_f32_e32 v221, v87
	v_add_f32_e32 v65, v217, v65
	v_exp_f32_e32 v222, v88
	v_add_f32_e32 v65, v219, v65
	v_exp_f32_e32 v223, v89
	v_add_f32_e32 v65, v220, v65
	v_exp_f32_e32 v224, v90
	v_add_f32_e32 v65, v221, v65
	v_exp_f32_e32 v225, v91
	v_add_f32_e32 v65, v222, v65
	v_exp_f32_e32 v226, v92
	v_exp_f32_e32 v82, v66
	v_exp_f32_e32 v66, v74
	s_lshl_b32 s12, s28, 7
	v_mul_u32_u24_e32 v74, 0x110, v211
	v_add_f32_e32 v65, v223, v65
	v_exp_f32_e32 v227, v93
	v_exp_f32_e32 v228, v94
	v_add3_u32 v94, v216, s12, v74
	v_add_f32_e32 v65, v224, v65
	v_add_u32_e32 v232, 0x8800, v94
	v_add_u32_e32 v233, 0xaa00, v94
	v_add_u32_e32 v236, 0xcc00, v94
	v_add_u32_e32 v237, 0xee00, v94
	v_add_f32_e32 v65, v225, v65
	v_exp_f32_e32 v229, v95
	v_exp_f32_e32 v230, v96
	v_exp_f32_e32 v231, v97
	v_exp_f32_e32 v83, v67
	v_exp_f32_e32 v84, v68
	v_exp_f32_e32 v85, v69
	v_exp_f32_e32 v86, v70
	v_exp_f32_e32 v87, v71
	v_exp_f32_e32 v88, v72
	v_exp_f32_e32 v89, v73
	v_exp_f32_e32 v67, v75
	v_exp_f32_e32 v68, v76
	v_exp_f32_e32 v69, v77
	v_exp_f32_e32 v70, v78
	v_exp_f32_e32 v71, v79
	v_exp_f32_e32 v72, v80
	v_exp_f32_e32 v73, v81
	ds_read_b128 v[74:77], v232
	ds_read_b128 v[78:81], v233
	ds_read_b128 v[90:93], v236
	ds_read_b128 v[94:97], v237
	v_cvt_pk_bf16_f32 v218, v196, v197
	v_cvt_pk_bf16_f32 v219, v217, v219
	v_cvt_pk_bf16_f32 v220, v220, v221
	v_cvt_pk_bf16_f32 v221, v222, v223
	v_add_f32_e32 v65, v226, v65
	s_waitcnt lgkmcnt(0)
	v_add_f32_e32 v65, v227, v65
	v_mfma_f32_32x32x16_bf16 v[0:15], v[74:77], v[218:221], v[0:15]
	v_add_f32_e32 v65, v228, v65
	v_add_f32_e32 v65, v229, v65
	v_add_f32_e32 v65, v230, v65
	v_add_f32_e32 v65, v231, v65
	v_add_f32_e32 v65, v82, v65
	v_add_f32_e32 v65, v83, v65
	v_add_f32_e32 v65, v84, v65
	v_mfma_f32_32x32x16_bf16 v[48:63], v[78:81], v[218:221], v[48:63]
	v_add_f32_e32 v65, v85, v65
	v_add_f32_e32 v65, v86, v65
	v_add_f32_e32 v65, v87, v65
	v_add_f32_e32 v65, v88, v65
	v_add_f32_e32 v65, v89, v65
	v_add_f32_e32 v65, v66, v65
	v_add_f32_e32 v65, v67, v65
	v_mfma_f32_32x32x16_bf16 v[32:47], v[90:93], v[218:221], v[32:47]
	v_cvt_pk_bf16_f32 v82, v82, v83
	v_cvt_pk_bf16_f32 v83, v84, v85
	v_cvt_pk_bf16_f32 v84, v86, v87
	v_cvt_pk_bf16_f32 v85, v88, v89
	v_add_f32_e32 v65, v68, v65
	v_add_f32_e32 v65, v69, v65
	v_add_f32_e32 v65, v70, v65
	v_mfma_f32_32x32x16_bf16 v[16:31], v[94:97], v[218:221], v[16:31]
	ds_read_b128 v[74:77], v232 offset:32
	ds_read_b128 v[78:81], v233 offset:32
	ds_read_b128 v[90:93], v236 offset:32
	ds_read_b128 v[94:97], v237 offset:32
	v_cvt_pk_bf16_f32 v218, v224, v225
	v_cvt_pk_bf16_f32 v219, v226, v227
	v_cvt_pk_bf16_f32 v220, v228, v229
	v_cvt_pk_bf16_f32 v221, v230, v231
	s_waitcnt lgkmcnt(0)
	v_add_f32_e32 v65, v71, v65
	v_add_f32_e32 v65, v72, v65
	v_mfma_f32_32x32x16_bf16 v[0:15], v[74:77], v[218:221], v[0:15]
	v_add_f32_e32 v65, v73, v65
	v_cvt_pk_bf16_f32 v66, v66, v67
	v_cvt_pk_bf16_f32 v67, v68, v69
	v_cvt_pk_bf16_f32 v68, v70, v71
	v_cvt_pk_bf16_f32 v69, v72, v73
	v_add_f32_e32 v212, v212, v65
	v_mfma_f32_32x32x16_bf16 v[48:63], v[78:81], v[218:221], v[48:63]
	v_mfma_f32_32x32x16_bf16 v[32:47], v[90:93], v[218:221], v[32:47]
	v_mfma_f32_32x32x16_bf16 v[16:31], v[94:97], v[218:221], v[16:31]
	ds_read_b128 v[74:77], v232 offset:64
	ds_read_b128 v[78:81], v233 offset:64
	ds_read_b128 v[90:93], v236 offset:64
	ds_read_b128 v[94:97], v237 offset:64
	s_waitcnt lgkmcnt(0)
	s_nop 0
	v_mfma_f32_32x32x16_bf16 v[0:15], v[74:77], v[82:85], v[0:15]
	v_mfma_f32_32x32x16_bf16 v[48:63], v[78:81], v[82:85], v[48:63]
	v_mfma_f32_32x32x16_bf16 v[32:47], v[90:93], v[82:85], v[32:47]
	v_mfma_f32_32x32x16_bf16 v[16:31], v[94:97], v[82:85], v[16:31]
	ds_read_b128 v[74:77], v232 offset:96
	ds_read_b128 v[78:81], v233 offset:96
	ds_read_b128 v[82:85], v236 offset:96
	ds_read_b128 v[86:89], v237 offset:96
	s_waitcnt lgkmcnt(1)
	v_mov_b64_e32 v[70:71], v[84:85]
	s_waitcnt lgkmcnt(0)
	v_mov_b64_e32 v[72:73], v[88:89]
	s_nop 0
	v_mov_b32_e32 v84, v70
	v_mov_b32_e32 v85, v71
	v_mov_b32_e32 v88, v72
	v_mov_b32_e32 v89, v73
	v_mfma_f32_32x32x16_bf16 v[0:15], v[74:77], v[66:69], v[0:15]
	v_mfma_f32_32x32x16_bf16 v[48:63], v[78:81], v[66:69], v[48:63]
	v_mfma_f32_32x32x16_bf16 v[32:47], v[82:85], v[66:69], v[32:47]
	v_mfma_f32_32x32x16_bf16 v[16:31], v[86:89], v[66:69], v[16:31]

;     ...
;         if (more && PV != 1) ATT_STORE(st ^ 1);
.LBB0_507:
	s_andn2_b64 vcc, exec, s[0:1]
	s_cbranch_vccnz .LBB0_509
	s_xor_b32 s0, s26, 1
	s_mul_i32 s0, s0, 0x11000
	s_add_i32 s0, s0, 0
	v_add_u32_e32 v65, s0, v154
	s_waitcnt vmcnt(7)
	ds_write_b128 v65, v[100:103]
	v_add_u32_e32 v65, s0, v158
	s_waitcnt vmcnt(6)
	ds_write_b128 v65, v[104:107]
	v_add_u32_e32 v65, s0, v162
	s_waitcnt vmcnt(5)
	ds_write_b128 v65, v[108:111]
	v_add_u32_e32 v65, s0, v166
	s_waitcnt vmcnt(4)
	ds_write_b128 v65, v[112:115]
	v_add_u32_e32 v65, s0, v172
	v_add_u32_e32 v65, 0x8800, v65
	s_waitcnt vmcnt(3)
	ds_write2_b64 v65, v[132:133], v[134:135] offset1:2
	v_add_u32_e32 v65, s0, v174
	v_add_u32_e32 v65, 0x8800, v65
	s_waitcnt vmcnt(2)
	ds_write2_b64 v65, v[136:137], v[138:139] offset1:2
	v_add_u32_e32 v65, s0, v176
	v_add_u32_e32 v65, 0x8800, v65
	s_waitcnt vmcnt(1)
	ds_write2_b64 v65, v[140:141], v[142:143] offset1:2
	v_add_u32_e32 v65, s0, v178
	v_add_u32_e32 v65, 0x8800, v65
	s_waitcnt vmcnt(0)
	ds_write2_b64 v65, v[144:145], v[146:147] offset1:2
